# FFN-up conv epilogue fully unrolled: one store base address per thread (32 consecutive rows via immediate offsets), no loop control
# speedup vs baseline: 1.0268x; 1.0134x over previous
.LBB0_683:
	s_or_b64 exec, exec, s[4:5]
	v_pk_mul_f32 v[2:3], v[2:3], v[66:67] op_sel_hi:[1,0]
	ds_write2_b32 v155, v2, v3 offset0:32 offset1:33
	v_pk_mul_f32 v[2:3], v[4:5], v[66:67] op_sel_hi:[1,0]
	ds_write2_b32 v155, v2, v3 offset0:34 offset1:35
	v_pk_mul_f32 v[2:3], v[6:7], v[66:67] op_sel_hi:[1,0]
	ds_write2_b32 v155, v2, v3 offset0:40 offset1:41
	v_pk_mul_f32 v[2:3], v[8:9], v[66:67] op_sel_hi:[1,0]
	ds_write2_b32 v155, v2, v3 offset0:42 offset1:43
	v_pk_mul_f32 v[2:3], v[10:11], v[66:67] op_sel_hi:[1,0]
	ds_write2_b32 v155, v2, v3 offset0:48 offset1:49
	v_pk_mul_f32 v[2:3], v[12:13], v[66:67] op_sel_hi:[1,0]
	s_load_dwordx8 s[4:11], s[0:1], 0xc0
	ds_write2_b32 v155, v2, v3 offset0:50 offset1:51
	v_pk_mul_f32 v[2:3], v[14:15], v[66:67] op_sel_hi:[1,0]
	ds_write2_b32 v155, v2, v3 offset0:56 offset1:57
	v_pk_mul_f32 v[2:3], v[16:17], v[66:67] op_sel_hi:[1,0]
	ds_write2_b32 v155, v2, v3 offset0:58 offset1:59
	v_lshl_or_b32 v2, s14, 6, v114
	v_ashrrev_i32_e32 v3, 31, v2
	v_lshlrev_b64 v[8:9], 2, v[2:3]
	s_waitcnt lgkmcnt(0)
	s_mov_b64 s[4:5], s[8:9]
	v_lshl_add_u64 v[10:11], s[4:5], 0, v[8:9]
	v_pk_mul_f32 v[18:19], v[18:19], v[66:67] op_sel_hi:[1,0]
	v_add_co_u32_e32 v4, vcc, s24, v10
	ds_write2_b32 v155, v18, v19 offset1:1
	v_pk_mul_f32 v[18:19], v[20:21], v[66:67] op_sel_hi:[1,0]
	v_addc_co_u32_e32 v5, vcc, 0, v11, vcc
	ds_write2_b32 v155, v18, v19 offset0:2 offset1:3
	v_pk_mul_f32 v[18:19], v[22:23], v[66:67] op_sel_hi:[1,0]
	v_add_co_u32_e32 v6, vcc, s28, v10
	ds_write2_b32 v155, v18, v19 offset0:8 offset1:9
	v_pk_mul_f32 v[18:19], v[24:25], v[66:67] op_sel_hi:[1,0]
	v_addc_co_u32_e32 v7, vcc, 0, v11, vcc
	ds_write2_b32 v155, v18, v19 offset0:10 offset1:11
	v_pk_mul_f32 v[18:19], v[26:27], v[66:67] op_sel_hi:[1,0]
	v_add_co_u32_e32 v14, vcc, s22, v10
	ds_write2_b32 v155, v18, v19 offset0:16 offset1:17
	v_pk_mul_f32 v[18:19], v[28:29], v[66:67] op_sel_hi:[1,0]
	v_addc_co_u32_e32 v15, vcc, 0, v11, vcc
	ds_write2_b32 v155, v18, v19 offset0:18 offset1:19
	v_pk_mul_f32 v[18:19], v[30:31], v[66:67] op_sel_hi:[1,0]
	v_add_co_u32_e32 v16, vcc, s29, v10
	ds_write2_b32 v155, v18, v19 offset0:24 offset1:25
	v_pk_mul_f32 v[18:19], v[32:33], v[66:67] op_sel_hi:[1,0]
	v_addc_co_u32_e32 v17, vcc, 0, v11, vcc
	ds_write2_b32 v155, v18, v19 offset0:26 offset1:27
	s_waitcnt lgkmcnt(0)
	s_barrier
	s_mov_b64 s[6:7], s[10:11]
	s_waitcnt vmcnt(0)
	v_mov_b32_e32 v3, v188
	s_nop 0
	v_mov_b32_e32 v5, v189
	s_nop 0
	v_mov_b32_e32 v7, v190
	v_add_co_u32_e32 v10, vcc, s33, v10
	v_lshl_add_u64 v[12:13], s[6:7], 0, v[8:9]
	s_nop 0
	v_addc_co_u32_e32 v11, vcc, 0, v11, vcc
	v_mov_b32_e32 v9, v191
	v_mov_b32_e32 v2, v192
	v_mov_b32_e32 v4, v193
	v_mov_b32_e32 v6, v194
	v_add_co_u32_e32 v10, vcc, s22, v12
	s_mul_i32 s4, s51, 0x7e
	s_nop 0
	v_addc_co_u32_e32 v11, vcc, 0, v13, vcc
	v_mov_b32_e32 v8, v195
	ds_read_b32 v15, v159
	ds_read_b32 v10, v160
	ds_read_b32 v14, v161
	ds_read_b32 v11, v162
	s_add_i32 s4, s21, s4
	s_mulk_i32 s52, 0x7c
	s_sub_i32 s10, s4, s52
	v_add_lshl_u32 v16, v167, s53, 6
	s_mov_b64 s[4:5], 0
	v_mov_b32_e32 v17, v158
	v_mov_b32_e32 v18, v156
	s_waitcnt vmcnt(0)
	s_add_i32 s63, s10, -2
	s_sub_i32 s64, s22, s50
	v_min_i32_e32 v40, s64, v157
	v_add_u32_e32 v40, s63, v40
	v_lshlrev_b32_e32 v41, 1, v114
	v_add_u32_e32 v32, s63, v18
	v_ashrrev_i32_e32 v220, 7, v32
	v_and_b32_e32 v24, 0x7f, v32
	v_mad_u32_u24 v220, v220, 44, s14
	v_subrev_u32_e32 v33, 64, v24
	v_lshlrev_b32_e32 v24, 7, v24
	v_sub_u32_e32 v34, v40, v32
	v_lshl_or_b32 v24, v220, 14, v24
	v_add_u32_e32 v39, v24, v41
	v_add_u32_e32 v35, 0xac000, v39
	v_add_u32_e32 v36, 1032, v17
	v_add_u32_e32 v37, 2064, v17
	v_add_u32_e32 v38, 3096, v17
	ds_read2_b32 v[188:189], v17 offset0:0 offset1:64
	ds_read2_b32 v[190:191], v17 offset0:129 offset1:193
	ds_read2_b32 v[192:193], v36 offset0:0 offset1:64
	ds_read2_b32 v[194:195], v36 offset0:129 offset1:193
	ds_read2_b32 v[196:197], v37 offset0:0 offset1:64
	ds_read2_b32 v[198:199], v37 offset0:129 offset1:193
	ds_read2_b32 v[200:201], v38 offset0:0 offset1:64
	ds_read2_b32 v[202:203], v38 offset0:129 offset1:193
	v_cmp_le_i32_e64 s[6:7], 63, v33
	v_cmp_le_i32_e64 s[8:9], 62, v33
	v_cmp_le_i32_e64 vcc, 61, v33
	v_cndmask_b32_e64 v25, v39, v35, s[6:7]
	v_cmp_le_i32_e64 s[6:7], 60, v33
	v_cndmask_b32_e64 v26, v39, v35, s[8:9]
	v_cmp_le_i32_e64 s[8:9], 59, v33
	v_cndmask_b32_e64 v27, v39, v35, vcc
	v_cmp_le_i32_e64 vcc, 58, v33
	v_cndmask_b32_e64 v28, v39, v35, s[6:7]
	v_cmp_le_i32_e64 s[6:7], 57, v33
	v_cndmask_b32_e64 v29, v39, v35, s[8:9]
	v_cndmask_b32_e64 v30, v39, v35, vcc
	s_nop 0
	v_cndmask_b32_e64 v31, v39, v35, s[6:7]
	v_mov_b32_e32 v24, v39
	s_waitcnt lgkmcnt(0)
	v_fma_f32 v204, v3, v15, v9
	v_fma_f32 v212, v2, v14, v8
	v_fma_f32 v205, v3, v10, v9
	v_fma_f32 v213, v2, v11, v8
	v_fma_f32 v206, v3, v188, v9
	v_fma_f32 v214, v2, v189, v8
	v_fma_f32 v207, v3, v190, v9
	v_fma_f32 v215, v2, v191, v8
	v_fma_f32 v208, v3, v192, v9
	v_fma_f32 v216, v2, v193, v8
	v_fma_f32 v209, v3, v194, v9
	v_fma_f32 v217, v2, v195, v8
	v_fma_f32 v210, v3, v196, v9
	v_fma_f32 v218, v2, v197, v8
	v_fma_f32 v211, v3, v198, v9
	v_fma_f32 v219, v2, v199, v8
	v_fma_f32 v204, v5, v10, v204
	v_fma_f32 v212, v4, v11, v212
	v_fma_f32 v205, v5, v188, v205
	v_fma_f32 v213, v4, v189, v213
	v_fma_f32 v206, v5, v190, v206
	v_fma_f32 v214, v4, v191, v214
	v_fma_f32 v207, v5, v192, v207
	v_fma_f32 v215, v4, v193, v215
	v_fma_f32 v208, v5, v194, v208
	v_fma_f32 v216, v4, v195, v216
	v_fma_f32 v209, v5, v196, v209
	v_fma_f32 v217, v4, v197, v217
	v_fma_f32 v210, v5, v198, v210
	v_fma_f32 v218, v4, v199, v218
	v_fma_f32 v211, v5, v200, v211
	v_fma_f32 v219, v4, v201, v219
	v_fma_f32 v204, v7, v188, v204
	v_fma_f32 v212, v6, v189, v212
	v_fma_f32 v205, v7, v190, v205
	v_fma_f32 v213, v6, v191, v213
	v_fma_f32 v206, v7, v192, v206
	v_fma_f32 v214, v6, v193, v214
	v_fma_f32 v207, v7, v194, v207
	v_fma_f32 v215, v6, v195, v215
	v_fma_f32 v208, v7, v196, v208
	v_fma_f32 v216, v6, v197, v216
	v_fma_f32 v209, v7, v198, v209
	v_fma_f32 v217, v6, v199, v217
	v_fma_f32 v210, v7, v200, v210
	v_fma_f32 v218, v6, v201, v218
	v_fma_f32 v211, v7, v202, v211
	v_fma_f32 v219, v6, v203, v219
	v_mul_f32_e32 v220, 0xbfb8aa3b, v204
	v_mul_f32_e32 v221, 0xbfb8aa3b, v205
	v_mul_f32_e32 v222, 0xbfb8aa3b, v206
	v_mul_f32_e32 v223, 0xbfb8aa3b, v207
	v_mul_f32_e32 v224, 0xbfb8aa3b, v208
	v_mul_f32_e32 v225, 0xbfb8aa3b, v209
	v_mul_f32_e32 v226, 0xbfb8aa3b, v210
	v_mul_f32_e32 v227, 0xbfb8aa3b, v211
	v_exp_f32_e32 v220, v220
	v_exp_f32_e32 v221, v221
	v_exp_f32_e32 v222, v222
	v_exp_f32_e32 v223, v223
	v_exp_f32_e32 v224, v224
	v_exp_f32_e32 v225, v225
	v_exp_f32_e32 v226, v226
	v_exp_f32_e32 v227, v227
	v_add_f32_e32 v220, 1.0, v220
	v_add_f32_e32 v221, 1.0, v221
	v_add_f32_e32 v222, 1.0, v222
	v_add_f32_e32 v223, 1.0, v223
	v_add_f32_e32 v224, 1.0, v224
	v_add_f32_e32 v225, 1.0, v225
	v_add_f32_e32 v226, 1.0, v226
	v_add_f32_e32 v227, 1.0, v227
	v_rcp_f32_e32 v220, v220
	v_rcp_f32_e32 v221, v221
	v_rcp_f32_e32 v222, v222
	v_rcp_f32_e32 v223, v223
	v_rcp_f32_e32 v224, v224
	v_rcp_f32_e32 v225, v225
	v_rcp_f32_e32 v226, v226
	v_rcp_f32_e32 v227, v227
	v_mov_b32_e32 v15, v200
	v_mov_b32_e32 v10, v202
	v_mov_b32_e32 v14, v201
	v_mov_b32_e32 v11, v203
	v_mul_f32_e32 v204, v204, v220
	v_mul_f32_e32 v205, v205, v221
	v_mul_f32_e32 v206, v206, v222
	v_mul_f32_e32 v207, v207, v223
	v_mul_f32_e32 v208, v208, v224
	v_mul_f32_e32 v209, v209, v225
	v_mul_f32_e32 v210, v210, v226
	v_mul_f32_e32 v211, v211, v227
	v_mul_f32_e32 v212, v212, v204
	v_mul_f32_e32 v213, v213, v205
	v_mul_f32_e32 v214, v214, v206
	v_mul_f32_e32 v215, v215, v207
	v_mul_f32_e32 v216, v216, v208
	v_mul_f32_e32 v217, v217, v209
	v_mul_f32_e32 v218, v218, v210
	v_mul_f32_e32 v219, v219, v211
	v_cvt_pk_bf16_f32 v212, v212, v213
	v_cvt_pk_bf16_f32 v214, v214, v215
	v_cvt_pk_bf16_f32 v216, v216, v217
	v_cvt_pk_bf16_f32 v218, v218, v219
	v_cmp_gt_i32_e32 vcc, 8, v34
	s_cmp_lg_u64 vcc, 0
	s_cbranch_scc1 .Lcv5_slow0
	global_store_short v24, v212, s[42:43]
	global_store_short_d16_hi v25, v212, s[42:43] offset:128
	global_store_short v26, v214, s[42:43] offset:256
	global_store_short_d16_hi v27, v214, s[42:43] offset:384
	global_store_short v28, v216, s[42:43] offset:512
	global_store_short_d16_hi v29, v216, s[42:43] offset:640
	global_store_short v30, v218, s[42:43] offset:768
	global_store_short_d16_hi v31, v218, s[42:43] offset:896
	s_branch .Lcv5_next0

.Lcv5_next0:
	v_add_u32_e32 v17, 0x1020, v17
	v_add_u32_e32 v36, 1032, v17
	v_add_u32_e32 v37, 2064, v17
	v_add_u32_e32 v38, 3096, v17
	ds_read2_b32 v[188:189], v17 offset0:0 offset1:64
	ds_read2_b32 v[190:191], v17 offset0:129 offset1:193
	ds_read2_b32 v[192:193], v36 offset0:0 offset1:64
	ds_read2_b32 v[194:195], v36 offset0:129 offset1:193
	ds_read2_b32 v[196:197], v37 offset0:0 offset1:64
	ds_read2_b32 v[198:199], v37 offset0:129 offset1:193
	ds_read2_b32 v[200:201], v38 offset0:0 offset1:64
	ds_read2_b32 v[202:203], v38 offset0:129 offset1:193
	v_cmp_le_i32_e64 s[6:7], 56, v33
	v_cmp_le_i32_e64 s[8:9], 55, v33
	v_cmp_le_i32_e64 vcc, 54, v33
	v_cndmask_b32_e64 v24, v39, v35, s[6:7]
	v_cmp_le_i32_e64 s[6:7], 53, v33
	v_cndmask_b32_e64 v25, v39, v35, s[8:9]
	v_cmp_le_i32_e64 s[8:9], 52, v33
	v_cndmask_b32_e64 v26, v39, v35, vcc
	v_cmp_le_i32_e64 vcc, 51, v33
	v_cndmask_b32_e64 v27, v39, v35, s[6:7]
	v_cmp_le_i32_e64 s[6:7], 50, v33
	v_cndmask_b32_e64 v28, v39, v35, s[8:9]
	v_cmp_le_i32_e64 s[8:9], 49, v33
	v_cndmask_b32_e64 v29, v39, v35, vcc
	v_cndmask_b32_e64 v30, v39, v35, s[6:7]
	s_nop 0
	v_cndmask_b32_e64 v31, v39, v35, s[8:9]
	s_waitcnt lgkmcnt(0)
	v_fma_f32 v204, v3, v15, v9
	v_fma_f32 v212, v2, v14, v8
	v_fma_f32 v205, v3, v10, v9
	v_fma_f32 v213, v2, v11, v8
	v_fma_f32 v206, v3, v188, v9
	v_fma_f32 v214, v2, v189, v8
	v_fma_f32 v207, v3, v190, v9
	v_fma_f32 v215, v2, v191, v8
	v_fma_f32 v208, v3, v192, v9
	v_fma_f32 v216, v2, v193, v8
	v_fma_f32 v209, v3, v194, v9
	v_fma_f32 v217, v2, v195, v8
	v_fma_f32 v210, v3, v196, v9
	v_fma_f32 v218, v2, v197, v8
	v_fma_f32 v211, v3, v198, v9
	v_fma_f32 v219, v2, v199, v8
	v_fma_f32 v204, v5, v10, v204
	v_fma_f32 v212, v4, v11, v212
	v_fma_f32 v205, v5, v188, v205
	v_fma_f32 v213, v4, v189, v213
	v_fma_f32 v206, v5, v190, v206
	v_fma_f32 v214, v4, v191, v214
	v_fma_f32 v207, v5, v192, v207
	v_fma_f32 v215, v4, v193, v215
	v_fma_f32 v208, v5, v194, v208
	v_fma_f32 v216, v4, v195, v216
	v_fma_f32 v209, v5, v196, v209
	v_fma_f32 v217, v4, v197, v217
	v_fma_f32 v210, v5, v198, v210
	v_fma_f32 v218, v4, v199, v218
	v_fma_f32 v211, v5, v200, v211
	v_fma_f32 v219, v4, v201, v219
	v_fma_f32 v204, v7, v188, v204
	v_fma_f32 v212, v6, v189, v212
	v_fma_f32 v205, v7, v190, v205
	v_fma_f32 v213, v6, v191, v213
	v_fma_f32 v206, v7, v192, v206
	v_fma_f32 v214, v6, v193, v214
	v_fma_f32 v207, v7, v194, v207
	v_fma_f32 v215, v6, v195, v215
	v_fma_f32 v208, v7, v196, v208
	v_fma_f32 v216, v6, v197, v216
	v_fma_f32 v209, v7, v198, v209
	v_fma_f32 v217, v6, v199, v217
	v_fma_f32 v210, v7, v200, v210
	v_fma_f32 v218, v6, v201, v218
	v_fma_f32 v211, v7, v202, v211
	v_fma_f32 v219, v6, v203, v219
	v_mul_f32_e32 v220, 0xbfb8aa3b, v204
	v_mul_f32_e32 v221, 0xbfb8aa3b, v205
	v_mul_f32_e32 v222, 0xbfb8aa3b, v206
	v_mul_f32_e32 v223, 0xbfb8aa3b, v207
	v_mul_f32_e32 v224, 0xbfb8aa3b, v208
	v_mul_f32_e32 v225, 0xbfb8aa3b, v209
	v_mul_f32_e32 v226, 0xbfb8aa3b, v210
	v_mul_f32_e32 v227, 0xbfb8aa3b, v211
	v_exp_f32_e32 v220, v220
	v_exp_f32_e32 v221, v221
	v_exp_f32_e32 v222, v222
	v_exp_f32_e32 v223, v223
	v_exp_f32_e32 v224, v224
	v_exp_f32_e32 v225, v225
	v_exp_f32_e32 v226, v226
	v_exp_f32_e32 v227, v227
	v_add_f32_e32 v220, 1.0, v220
	v_add_f32_e32 v221, 1.0, v221
	v_add_f32_e32 v222, 1.0, v222
	v_add_f32_e32 v223, 1.0, v223
	v_add_f32_e32 v224, 1.0, v224
	v_add_f32_e32 v225, 1.0, v225
	v_add_f32_e32 v226, 1.0, v226
	v_add_f32_e32 v227, 1.0, v227
	v_rcp_f32_e32 v220, v220
	v_rcp_f32_e32 v221, v221
	v_rcp_f32_e32 v222, v222
	v_rcp_f32_e32 v223, v223
	v_rcp_f32_e32 v224, v224
	v_rcp_f32_e32 v225, v225
	v_rcp_f32_e32 v226, v226
	v_rcp_f32_e32 v227, v227
	v_mov_b32_e32 v15, v200
	v_mov_b32_e32 v10, v202
	v_mov_b32_e32 v14, v201
	v_mov_b32_e32 v11, v203
	v_mul_f32_e32 v204, v204, v220
	v_mul_f32_e32 v205, v205, v221
	v_mul_f32_e32 v206, v206, v222
	v_mul_f32_e32 v207, v207, v223
	v_mul_f32_e32 v208, v208, v224
	v_mul_f32_e32 v209, v209, v225
	v_mul_f32_e32 v210, v210, v226
	v_mul_f32_e32 v211, v211, v227
	v_mul_f32_e32 v212, v212, v204
	v_mul_f32_e32 v213, v213, v205
	v_mul_f32_e32 v214, v214, v206
	v_mul_f32_e32 v215, v215, v207
	v_mul_f32_e32 v216, v216, v208
	v_mul_f32_e32 v217, v217, v209
	v_mul_f32_e32 v218, v218, v210
	v_mul_f32_e32 v219, v219, v211
	v_cvt_pk_bf16_f32 v212, v212, v213
	v_cvt_pk_bf16_f32 v214, v214, v215
	v_cvt_pk_bf16_f32 v216, v216, v217
	v_cvt_pk_bf16_f32 v218, v218, v219
	v_cmp_gt_i32_e32 vcc, 16, v34
	s_cmp_lg_u64 vcc, 0
	s_cbranch_scc1 .Lcv5_slow1
	global_store_short v24, v212, s[42:43] offset:1024
	global_store_short_d16_hi v25, v212, s[42:43] offset:1152
	global_store_short v26, v214, s[42:43] offset:1280
	global_store_short_d16_hi v27, v214, s[42:43] offset:1408
	global_store_short v28, v216, s[42:43] offset:1536
	global_store_short_d16_hi v29, v216, s[42:43] offset:1664
	global_store_short v30, v218, s[42:43] offset:1792
	global_store_short_d16_hi v31, v218, s[42:43] offset:1920
	s_branch .Lcv5_next1
.Lcv5_slow1:
	v_cmp_lt_i32_e32 vcc, 8, v34
	s_and_b64 exec, exec, vcc
	global_store_short v24, v212, s[42:43] offset:1024
	v_cmp_lt_i32_e32 vcc, 9, v34
	s_and_b64 exec, exec, vcc
	global_store_short_d16_hi v25, v212, s[42:43] offset:1152
	v_cmp_lt_i32_e32 vcc, 10, v34
	s_and_b64 exec, exec, vcc
	global_store_short v26, v214, s[42:43] offset:1280
	v_cmp_lt_i32_e32 vcc, 11, v34
	s_and_b64 exec, exec, vcc
	global_store_short_d16_hi v27, v214, s[42:43] offset:1408
	v_cmp_lt_i32_e32 vcc, 12, v34
	s_and_b64 exec, exec, vcc
	global_store_short v28, v216, s[42:43] offset:1536
	v_cmp_lt_i32_e32 vcc, 13, v34
	s_and_b64 exec, exec, vcc
	global_store_short_d16_hi v29, v216, s[42:43] offset:1664
	v_cmp_lt_i32_e32 vcc, 14, v34
	s_and_b64 exec, exec, vcc
	global_store_short v30, v218, s[42:43] offset:1792
	v_cmp_lt_i32_e32 vcc, 15, v34
	s_and_b64 exec, exec, vcc
	global_store_short_d16_hi v31, v218, s[42:43] offset:1920
	s_mov_b64 exec, -1
.Lcv5_next1:
	v_add_u32_e32 v17, 0x1020, v17
	v_add_u32_e32 v36, 1032, v17
	v_add_u32_e32 v37, 2064, v17
	v_add_u32_e32 v38, 3096, v17
	ds_read2_b32 v[188:189], v17 offset0:0 offset1:64
	ds_read2_b32 v[190:191], v17 offset0:129 offset1:193
	ds_read2_b32 v[192:193], v36 offset0:0 offset1:64
	ds_read2_b32 v[194:195], v36 offset0:129 offset1:193
	ds_read2_b32 v[196:197], v37 offset0:0 offset1:64
	ds_read2_b32 v[198:199], v37 offset0:129 offset1:193
	ds_read2_b32 v[200:201], v38 offset0:0 offset1:64
	ds_read2_b32 v[202:203], v38 offset0:129 offset1:193
	v_cmp_le_i32_e64 s[6:7], 48, v33
	v_cmp_le_i32_e64 s[8:9], 47, v33
	v_cmp_le_i32_e64 vcc, 46, v33
	v_cndmask_b32_e64 v24, v39, v35, s[6:7]
	v_cmp_le_i32_e64 s[6:7], 45, v33
	v_cndmask_b32_e64 v25, v39, v35, s[8:9]
	v_cmp_le_i32_e64 s[8:9], 44, v33
	v_cndmask_b32_e64 v26, v39, v35, vcc
	v_cmp_le_i32_e64 vcc, 43, v33
	v_cndmask_b32_e64 v27, v39, v35, s[6:7]
	v_cmp_le_i32_e64 s[6:7], 42, v33
	v_cndmask_b32_e64 v28, v39, v35, s[8:9]
	v_cmp_le_i32_e64 s[8:9], 41, v33
	v_cndmask_b32_e64 v29, v39, v35, vcc
	v_cndmask_b32_e64 v30, v39, v35, s[6:7]
	s_nop 0
	v_cndmask_b32_e64 v31, v39, v35, s[8:9]
	s_waitcnt lgkmcnt(0)
	v_fma_f32 v204, v3, v15, v9
	v_fma_f32 v212, v2, v14, v8
	v_fma_f32 v205, v3, v10, v9
	v_fma_f32 v213, v2, v11, v8
	v_fma_f32 v206, v3, v188, v9
	v_fma_f32 v214, v2, v189, v8
	v_fma_f32 v207, v3, v190, v9
	v_fma_f32 v215, v2, v191, v8
	v_fma_f32 v208, v3, v192, v9
	v_fma_f32 v216, v2, v193, v8
	v_fma_f32 v209, v3, v194, v9
	v_fma_f32 v217, v2, v195, v8
	v_fma_f32 v210, v3, v196, v9
	v_fma_f32 v218, v2, v197, v8
	v_fma_f32 v211, v3, v198, v9
	v_fma_f32 v219, v2, v199, v8
	v_fma_f32 v204, v5, v10, v204
	v_fma_f32 v212, v4, v11, v212
	v_fma_f32 v205, v5, v188, v205
	v_fma_f32 v213, v4, v189, v213
	v_fma_f32 v206, v5, v190, v206
	v_fma_f32 v214, v4, v191, v214
	v_fma_f32 v207, v5, v192, v207
	v_fma_f32 v215, v4, v193, v215
	v_fma_f32 v208, v5, v194, v208
	v_fma_f32 v216, v4, v195, v216
	v_fma_f32 v209, v5, v196, v209
	v_fma_f32 v217, v4, v197, v217
	v_fma_f32 v210, v5, v198, v210
	v_fma_f32 v218, v4, v199, v218
	v_fma_f32 v211, v5, v200, v211
	v_fma_f32 v219, v4, v201, v219
	v_fma_f32 v204, v7, v188, v204
	v_fma_f32 v212, v6, v189, v212
	v_fma_f32 v205, v7, v190, v205
	v_fma_f32 v213, v6, v191, v213
	v_fma_f32 v206, v7, v192, v206
	v_fma_f32 v214, v6, v193, v214
	v_fma_f32 v207, v7, v194, v207
	v_fma_f32 v215, v6, v195, v215
	v_fma_f32 v208, v7, v196, v208
	v_fma_f32 v216, v6, v197, v216
	v_fma_f32 v209, v7, v198, v209
	v_fma_f32 v217, v6, v199, v217
	v_fma_f32 v210, v7, v200, v210
	v_fma_f32 v218, v6, v201, v218
	v_fma_f32 v211, v7, v202, v211
	v_fma_f32 v219, v6, v203, v219
	v_mul_f32_e32 v220, 0xbfb8aa3b, v204
	v_mul_f32_e32 v221, 0xbfb8aa3b, v205
	v_mul_f32_e32 v222, 0xbfb8aa3b, v206
	v_mul_f32_e32 v223, 0xbfb8aa3b, v207
	v_mul_f32_e32 v224, 0xbfb8aa3b, v208
	v_mul_f32_e32 v225, 0xbfb8aa3b, v209
	v_mul_f32_e32 v226, 0xbfb8aa3b, v210
	v_mul_f32_e32 v227, 0xbfb8aa3b, v211
	v_exp_f32_e32 v220, v220
	v_exp_f32_e32 v221, v221
	v_exp_f32_e32 v222, v222
	v_exp_f32_e32 v223, v223
	v_exp_f32_e32 v224, v224
	v_exp_f32_e32 v225, v225
	v_exp_f32_e32 v226, v226
	v_exp_f32_e32 v227, v227
	v_add_f32_e32 v220, 1.0, v220
	v_add_f32_e32 v221, 1.0, v221
	v_add_f32_e32 v222, 1.0, v222
	v_add_f32_e32 v223, 1.0, v223
	v_add_f32_e32 v224, 1.0, v224
	v_add_f32_e32 v225, 1.0, v225
	v_add_f32_e32 v226, 1.0, v226
	v_add_f32_e32 v227, 1.0, v227
	v_rcp_f32_e32 v220, v220
	v_rcp_f32_e32 v221, v221
	v_rcp_f32_e32 v222, v222
	v_rcp_f32_e32 v223, v223
	v_rcp_f32_e32 v224, v224
	v_rcp_f32_e32 v225, v225
	v_rcp_f32_e32 v226, v226
	v_rcp_f32_e32 v227, v227
	v_mov_b32_e32 v15, v200
	v_mov_b32_e32 v10, v202
	v_mov_b32_e32 v14, v201
	v_mov_b32_e32 v11, v203
	v_mul_f32_e32 v204, v204, v220
	v_mul_f32_e32 v205, v205, v221
	v_mul_f32_e32 v206, v206, v222
	v_mul_f32_e32 v207, v207, v223
	v_mul_f32_e32 v208, v208, v224
	v_mul_f32_e32 v209, v209, v225
	v_mul_f32_e32 v210, v210, v226
	v_mul_f32_e32 v211, v211, v227
	v_mul_f32_e32 v212, v212, v204
	v_mul_f32_e32 v213, v213, v205
	v_mul_f32_e32 v214, v214, v206
	v_mul_f32_e32 v215, v215, v207
	v_mul_f32_e32 v216, v216, v208
	v_mul_f32_e32 v217, v217, v209
	v_mul_f32_e32 v218, v218, v210
	v_mul_f32_e32 v219, v219, v211
	v_cvt_pk_bf16_f32 v212, v212, v213
	v_cvt_pk_bf16_f32 v214, v214, v215
	v_cvt_pk_bf16_f32 v216, v216, v217
	v_cvt_pk_bf16_f32 v218, v218, v219
	v_cmp_gt_i32_e32 vcc, 24, v34
	s_cmp_lg_u64 vcc, 0
	s_cbranch_scc1 .Lcv5_slow2
	global_store_short v24, v212, s[42:43] offset:2048
	global_store_short_d16_hi v25, v212, s[42:43] offset:2176
	global_store_short v26, v214, s[42:43] offset:2304
	global_store_short_d16_hi v27, v214, s[42:43] offset:2432
	global_store_short v28, v216, s[42:43] offset:2560
	global_store_short_d16_hi v29, v216, s[42:43] offset:2688
	global_store_short v30, v218, s[42:43] offset:2816
	global_store_short_d16_hi v31, v218, s[42:43] offset:2944
	s_branch .Lcv5_next2
.Lcv5_slow2:
	v_cmp_lt_i32_e32 vcc, 16, v34
	s_and_b64 exec, exec, vcc
	global_store_short v24, v212, s[42:43] offset:2048
	v_cmp_lt_i32_e32 vcc, 17, v34
	s_and_b64 exec, exec, vcc
	global_store_short_d16_hi v25, v212, s[42:43] offset:2176
	v_cmp_lt_i32_e32 vcc, 18, v34
	s_and_b64 exec, exec, vcc
	global_store_short v26, v214, s[42:43] offset:2304
	v_cmp_lt_i32_e32 vcc, 19, v34
	s_and_b64 exec, exec, vcc
	global_store_short_d16_hi v27, v214, s[42:43] offset:2432
	v_cmp_lt_i32_e32 vcc, 20, v34
	s_and_b64 exec, exec, vcc
	global_store_short v28, v216, s[42:43] offset:2560
	v_cmp_lt_i32_e32 vcc, 21, v34
	s_and_b64 exec, exec, vcc
	global_store_short_d16_hi v29, v216, s[42:43] offset:2688
	v_cmp_lt_i32_e32 vcc, 22, v34
	s_and_b64 exec, exec, vcc
	global_store_short v30, v218, s[42:43] offset:2816
	v_cmp_lt_i32_e32 vcc, 23, v34
	s_and_b64 exec, exec, vcc
	global_store_short_d16_hi v31, v218, s[42:43] offset:2944
	s_mov_b64 exec, -1
.Lcv5_next2:
	v_add_u32_e32 v17, 0x1020, v17
	v_add_u32_e32 v36, 1032, v17
	v_add_u32_e32 v37, 2064, v17
	v_add_u32_e32 v38, 3096, v17
	ds_read2_b32 v[188:189], v17 offset0:0 offset1:64
	ds_read2_b32 v[190:191], v17 offset0:129 offset1:193
	ds_read2_b32 v[192:193], v36 offset0:0 offset1:64
	ds_read2_b32 v[194:195], v36 offset0:129 offset1:193
	ds_read2_b32 v[196:197], v37 offset0:0 offset1:64
	ds_read2_b32 v[198:199], v37 offset0:129 offset1:193
	ds_read2_b32 v[200:201], v38 offset0:0 offset1:64
	ds_read2_b32 v[202:203], v38 offset0:129 offset1:193
	v_cmp_le_i32_e64 s[6:7], 40, v33
	v_cmp_le_i32_e64 s[8:9], 39, v33
	v_cmp_le_i32_e64 vcc, 38, v33
	v_cndmask_b32_e64 v24, v39, v35, s[6:7]
	v_cmp_le_i32_e64 s[6:7], 37, v33
	v_cndmask_b32_e64 v25, v39, v35, s[8:9]
	v_cmp_le_i32_e64 s[8:9], 36, v33
	v_cndmask_b32_e64 v26, v39, v35, vcc
	v_cmp_le_i32_e64 vcc, 35, v33
	v_cndmask_b32_e64 v27, v39, v35, s[6:7]
	v_cmp_le_i32_e64 s[6:7], 34, v33
	v_cndmask_b32_e64 v28, v39, v35, s[8:9]
	v_cmp_le_i32_e64 s[8:9], 33, v33
	v_cndmask_b32_e64 v29, v39, v35, vcc
	v_cndmask_b32_e64 v30, v39, v35, s[6:7]
	s_nop 0
	v_cndmask_b32_e64 v31, v39, v35, s[8:9]
	s_waitcnt lgkmcnt(0)
	v_fma_f32 v204, v3, v15, v9
	v_fma_f32 v212, v2, v14, v8
	v_fma_f32 v205, v3, v10, v9
	v_fma_f32 v213, v2, v11, v8
	v_fma_f32 v206, v3, v188, v9
	v_fma_f32 v214, v2, v189, v8
	v_fma_f32 v207, v3, v190, v9
	v_fma_f32 v215, v2, v191, v8
	v_fma_f32 v208, v3, v192, v9
	v_fma_f32 v216, v2, v193, v8
	v_fma_f32 v209, v3, v194, v9
	v_fma_f32 v217, v2, v195, v8
	v_fma_f32 v210, v3, v196, v9
	v_fma_f32 v218, v2, v197, v8
	v_fma_f32 v211, v3, v198, v9
	v_fma_f32 v219, v2, v199, v8
	v_fma_f32 v204, v5, v10, v204
	v_fma_f32 v212, v4, v11, v212
	v_fma_f32 v205, v5, v188, v205
	v_fma_f32 v213, v4, v189, v213
	v_fma_f32 v206, v5, v190, v206
	v_fma_f32 v214, v4, v191, v214
	v_fma_f32 v207, v5, v192, v207
	v_fma_f32 v215, v4, v193, v215
	v_fma_f32 v208, v5, v194, v208
	v_fma_f32 v216, v4, v195, v216
	v_fma_f32 v209, v5, v196, v209
	v_fma_f32 v217, v4, v197, v217
	v_fma_f32 v210, v5, v198, v210
	v_fma_f32 v218, v4, v199, v218
	v_fma_f32 v211, v5, v200, v211
	v_fma_f32 v219, v4, v201, v219
	v_fma_f32 v204, v7, v188, v204
	v_fma_f32 v212, v6, v189, v212
	v_fma_f32 v205, v7, v190, v205
	v_fma_f32 v213, v6, v191, v213
	v_fma_f32 v206, v7, v192, v206
	v_fma_f32 v214, v6, v193, v214
	v_fma_f32 v207, v7, v194, v207
	v_fma_f32 v215, v6, v195, v215
	v_fma_f32 v208, v7, v196, v208
	v_fma_f32 v216, v6, v197, v216
	v_fma_f32 v209, v7, v198, v209
	v_fma_f32 v217, v6, v199, v217
	v_fma_f32 v210, v7, v200, v210
	v_fma_f32 v218, v6, v201, v218
	v_fma_f32 v211, v7, v202, v211
	v_fma_f32 v219, v6, v203, v219
	v_mul_f32_e32 v220, 0xbfb8aa3b, v204
	v_mul_f32_e32 v221, 0xbfb8aa3b, v205
	v_mul_f32_e32 v222, 0xbfb8aa3b, v206
	v_mul_f32_e32 v223, 0xbfb8aa3b, v207
	v_mul_f32_e32 v224, 0xbfb8aa3b, v208
	v_mul_f32_e32 v225, 0xbfb8aa3b, v209
	v_mul_f32_e32 v226, 0xbfb8aa3b, v210
	v_mul_f32_e32 v227, 0xbfb8aa3b, v211
	v_exp_f32_e32 v220, v220
	v_exp_f32_e32 v221, v221
	v_exp_f32_e32 v222, v222
	v_exp_f32_e32 v223, v223
	v_exp_f32_e32 v224, v224
	v_exp_f32_e32 v225, v225
	v_exp_f32_e32 v226, v226
	v_exp_f32_e32 v227, v227
	v_add_f32_e32 v220, 1.0, v220
	v_add_f32_e32 v221, 1.0, v221
	v_add_f32_e32 v222, 1.0, v222
	v_add_f32_e32 v223, 1.0, v223
	v_add_f32_e32 v224, 1.0, v224
	v_add_f32_e32 v225, 1.0, v225
	v_add_f32_e32 v226, 1.0, v226
	v_add_f32_e32 v227, 1.0, v227
	v_rcp_f32_e32 v220, v220
	v_rcp_f32_e32 v221, v221
	v_rcp_f32_e32 v222, v222
	v_rcp_f32_e32 v223, v223
	v_rcp_f32_e32 v224, v224
	v_rcp_f32_e32 v225, v225
	v_rcp_f32_e32 v226, v226
	v_rcp_f32_e32 v227, v227
	v_mul_f32_e32 v204, v204, v220
	v_mul_f32_e32 v205, v205, v221
	v_mul_f32_e32 v206, v206, v222
	v_mul_f32_e32 v207, v207, v223
	v_mul_f32_e32 v208, v208, v224
	v_mul_f32_e32 v209, v209, v225
	v_mul_f32_e32 v210, v210, v226
	v_mul_f32_e32 v211, v211, v227
	v_mul_f32_e32 v212, v212, v204
	v_mul_f32_e32 v213, v213, v205
	v_mul_f32_e32 v214, v214, v206
	v_mul_f32_e32 v215, v215, v207
	v_mul_f32_e32 v216, v216, v208
	v_mul_f32_e32 v217, v217, v209
	v_mul_f32_e32 v218, v218, v210
	v_mul_f32_e32 v219, v219, v211
	v_cvt_pk_bf16_f32 v212, v212, v213
	v_cvt_pk_bf16_f32 v214, v214, v215
	v_cvt_pk_bf16_f32 v216, v216, v217
	v_cvt_pk_bf16_f32 v218, v218, v219
	v_cmp_gt_i32_e32 vcc, 32, v34
	s_cmp_lg_u64 vcc, 0
	s_cbranch_scc1 .Lcv5_slow3
	global_store_short v24, v212, s[42:43] offset:3072
	global_store_short_d16_hi v25, v212, s[42:43] offset:3200
	global_store_short v26, v214, s[42:43] offset:3328
	global_store_short_d16_hi v27, v214, s[42:43] offset:3456
	global_store_short v28, v216, s[42:43] offset:3584
	global_store_short_d16_hi v29, v216, s[42:43] offset:3712
	global_store_short v30, v218, s[42:43] offset:3840
	global_store_short_d16_hi v31, v218, s[42:43] offset:3968
	s_branch .Lcv5_next3
.Lcv5_slow3:
	v_cmp_lt_i32_e32 vcc, 24, v34
	s_and_b64 exec, exec, vcc
	global_store_short v24, v212, s[42:43] offset:3072
	v_cmp_lt_i32_e32 vcc, 25, v34
	s_and_b64 exec, exec, vcc
	global_store_short_d16_hi v25, v212, s[42:43] offset:3200
	v_cmp_lt_i32_e32 vcc, 26, v34
	s_and_b64 exec, exec, vcc
	global_store_short v26, v214, s[42:43] offset:3328
	v_cmp_lt_i32_e32 vcc, 27, v34
	s_and_b64 exec, exec, vcc
	global_store_short_d16_hi v27, v214, s[42:43] offset:3456
	v_cmp_lt_i32_e32 vcc, 28, v34
	s_and_b64 exec, exec, vcc
	global_store_short v28, v216, s[42:43] offset:3584
	v_cmp_lt_i32_e32 vcc, 29, v34
	s_and_b64 exec, exec, vcc
	global_store_short_d16_hi v29, v216, s[42:43] offset:3712
	v_cmp_lt_i32_e32 vcc, 30, v34
	s_and_b64 exec, exec, vcc
	global_store_short v30, v218, s[42:43] offset:3840
	v_cmp_lt_i32_e32 vcc, 31, v34
	s_and_b64 exec, exec, vcc
	global_store_short_d16_hi v31, v218, s[42:43] offset:3968
	s_mov_b64 exec, -1
.Lcv5_next3:
	s_branch .LBB0_646
.LBB0_687:
	s_load_dwordx2 s[6:7], s[0:1], 0xf8
	s_waitcnt lgkmcnt(0)
	s_cmp_gt_i32 s7, 6
	s_cselect_b64 s[4:5], -1, 0
	s_and_b64 s[2:3], s[12:13], s[4:5]
	s_andn2_b64 vcc, exec, s[2:3]
	s_cbranch_vccnz .LBB0_755
	s_cmpk_lt_u32 s7, 0x3e9
	s_mov_b64 s[6:7], -1
	s_cbranch_scc0 .LBB0_742
	s_waitcnt vmcnt(0)
	s_barrier
	s_mov_b64 s[6:7], exec
	v_readlane_b32 s2, v231, 0
	v_readlane_b32 s3, v231, 1
	s_and_b64 s[2:3], s[6:7], s[2:3]
	s_mov_b64 exec, s[2:3]
	s_cbranch_execz .LBB0_741
	v_mov_b32_e32 v1, 0x12000
	s_waitcnt vmcnt(0) expcnt(0) lgkmcnt(0)
	ds_read_b32 v3, v1
	v_mov_b32_e32 v1, 0x12004
	ds_read_b32 v1, v1
	s_waitcnt lgkmcnt(1)
	v_cmp_ne_u32_e32 vcc, 0, v3
	s_cbranch_vccnz .LBB0_705
	s_load_dwordx2 s[2:3], s[0:1], 0x100
	s_load_dword s11, s[0:1], 0x108
	s_add_u32 s8, s34, 0x1000
	s_addc_u32 s9, s35, 0
	s_add_u32 s10, s34, 0x1100
	s_waitcnt lgkmcnt(0)
	s_mul_i32 s2, s3, s2
	s_mul_i32 s2, s2, s11
	s_addc_u32 s11, s35, 0
	s_add_u32 s12, s34, 0x1200
	s_addc_u32 s13, s35, 0
	s_add_u32 s14, s34, 0x1300
	s_addc_u32 s15, s35, 0
	s_mov_b32 s3, 1
	v_mov_b32_e32 v17, 0
	s_branch .LBB0_693

.LBB0_2400:
	s_or_b64 exec, exec, s[4:5]
	v_pk_mul_f32 v[2:3], v[2:3], v[66:67] op_sel_hi:[1,0]
	ds_write2_b32 v155, v2, v3 offset0:32 offset1:33
	v_pk_mul_f32 v[2:3], v[4:5], v[66:67] op_sel_hi:[1,0]
	ds_write2_b32 v155, v2, v3 offset0:34 offset1:35
	v_pk_mul_f32 v[2:3], v[6:7], v[66:67] op_sel_hi:[1,0]
	ds_write2_b32 v155, v2, v3 offset0:40 offset1:41
	v_pk_mul_f32 v[2:3], v[8:9], v[66:67] op_sel_hi:[1,0]
	ds_write2_b32 v155, v2, v3 offset0:42 offset1:43
	v_pk_mul_f32 v[2:3], v[10:11], v[66:67] op_sel_hi:[1,0]
	ds_write2_b32 v155, v2, v3 offset0:48 offset1:49
	v_pk_mul_f32 v[2:3], v[12:13], v[66:67] op_sel_hi:[1,0]
	ds_write2_b32 v155, v2, v3 offset0:50 offset1:51
	v_pk_mul_f32 v[2:3], v[14:15], v[66:67] op_sel_hi:[1,0]
	ds_write2_b32 v155, v2, v3 offset0:56 offset1:57
	v_pk_mul_f32 v[2:3], v[16:17], v[66:67] op_sel_hi:[1,0]
	v_pk_mul_f32 v[18:19], v[18:19], v[66:67] op_sel_hi:[1,0]
	ds_write2_b32 v155, v2, v3 offset0:58 offset1:59
	v_lshl_or_b32 v2, s18, 6, v114
	ds_write2_b32 v155, v18, v19 offset1:1
	v_pk_mul_f32 v[18:19], v[20:21], v[66:67] op_sel_hi:[1,0]
	v_ashrrev_i32_e32 v3, 31, v2
	ds_write2_b32 v155, v18, v19 offset0:2 offset1:3
	v_pk_mul_f32 v[18:19], v[22:23], v[66:67] op_sel_hi:[1,0]
	v_lshlrev_b64 v[8:9], 2, v[2:3]
	ds_write2_b32 v155, v18, v19 offset0:8 offset1:9
	v_pk_mul_f32 v[18:19], v[24:25], v[66:67] op_sel_hi:[1,0]
	v_lshl_add_u64 v[10:11], s[14:15], 0, v[8:9]
	ds_write2_b32 v155, v18, v19 offset0:10 offset1:11
	v_pk_mul_f32 v[18:19], v[26:27], v[66:67] op_sel_hi:[1,0]
	v_add_co_u32_e32 v12, vcc, s28, v10
	ds_write2_b32 v155, v18, v19 offset0:16 offset1:17
	v_pk_mul_f32 v[18:19], v[28:29], v[66:67] op_sel_hi:[1,0]
	v_addc_co_u32_e32 v13, vcc, 0, v11, vcc
	ds_write2_b32 v155, v18, v19 offset0:18 offset1:19
	v_pk_mul_f32 v[18:19], v[30:31], v[66:67] op_sel_hi:[1,0]
	v_add_co_u32_e32 v14, vcc, s30, v10
	ds_write2_b32 v155, v18, v19 offset0:24 offset1:25
	v_pk_mul_f32 v[18:19], v[32:33], v[66:67] op_sel_hi:[1,0]
	v_addc_co_u32_e32 v15, vcc, 0, v11, vcc
	ds_write2_b32 v155, v18, v19 offset0:26 offset1:27
	s_waitcnt lgkmcnt(0)
	s_barrier
	s_waitcnt vmcnt(0)
	v_mov_b32_e32 v3, v188
	v_mov_b32_e32 v5, v189
	v_mov_b32_e32 v7, v190
	v_add_co_u32_e32 v14, vcc, s26, v10
	v_lshl_add_u64 v[12:13], s[16:17], 0, v[8:9]
	s_nop 0
	v_addc_co_u32_e32 v15, vcc, 0, v11, vcc
	v_add_co_u32_e32 v16, vcc, s31, v10
	v_mov_b32_e32 v9, v191
	s_nop 0
	v_addc_co_u32_e32 v17, vcc, 0, v11, vcc
	v_add_co_u32_e32 v10, vcc, s33, v10
	s_mul_i32 s4, s37, 0x7e
	s_nop 0
	v_addc_co_u32_e32 v11, vcc, 0, v11, vcc
	v_mov_b32_e32 v2, v192
	v_mov_b32_e32 v4, v193
	v_mov_b32_e32 v6, v194
	v_add_co_u32_e32 v10, vcc, s26, v12
	s_add_i32 s4, s25, s4
	s_nop 0
	v_addc_co_u32_e32 v11, vcc, 0, v13, vcc
	v_mov_b32_e32 v8, v195
	ds_read_b32 v15, v159
	ds_read_b32 v10, v160
	ds_read_b32 v14, v161
	ds_read_b32 v11, v162
	s_mulk_i32 s38, 0x7c
	s_sub_i32 s10, s4, s38
	v_add_lshl_u32 v16, v167, s39, 6
	s_mov_b64 s[4:5], 0
	v_mov_b32_e32 v17, v158
	v_mov_b32_e32 v18, v156
	s_waitcnt vmcnt(0)
	s_add_i32 s63, s10, -2
	s_sub_i32 s64, s26, s36
	v_min_i32_e32 v40, s64, v157
	v_add_u32_e32 v40, s63, v40
	v_lshlrev_b32_e32 v41, 1, v114
	v_add_u32_e32 v32, s63, v18
	v_ashrrev_i32_e32 v220, 7, v32
	v_and_b32_e32 v24, 0x7f, v32
	v_mad_u32_u24 v220, v220, 44, s18
	v_subrev_u32_e32 v33, 64, v24
	v_lshlrev_b32_e32 v24, 7, v24
	v_sub_u32_e32 v34, v40, v32
	v_lshl_or_b32 v24, v220, 14, v24
	v_add_u32_e32 v39, v24, v41
	v_add_u32_e32 v35, 0xac000, v39
	v_add_u32_e32 v36, 1032, v17
	v_add_u32_e32 v37, 2064, v17
	v_add_u32_e32 v38, 3096, v17
	ds_read2_b32 v[188:189], v17 offset0:0 offset1:64
	ds_read2_b32 v[190:191], v17 offset0:129 offset1:193
	ds_read2_b32 v[192:193], v36 offset0:0 offset1:64
	ds_read2_b32 v[194:195], v36 offset0:129 offset1:193
	ds_read2_b32 v[196:197], v37 offset0:0 offset1:64
	ds_read2_b32 v[198:199], v37 offset0:129 offset1:193
	ds_read2_b32 v[200:201], v38 offset0:0 offset1:64
	ds_read2_b32 v[202:203], v38 offset0:129 offset1:193
	v_cmp_le_i32_e64 s[6:7], 63, v33
	v_cmp_le_i32_e64 s[8:9], 62, v33
	v_cmp_le_i32_e64 vcc, 61, v33
	v_cndmask_b32_e64 v25, v39, v35, s[6:7]
	v_cmp_le_i32_e64 s[6:7], 60, v33
	v_cndmask_b32_e64 v26, v39, v35, s[8:9]
	v_cmp_le_i32_e64 s[8:9], 59, v33
	v_cndmask_b32_e64 v27, v39, v35, vcc
	v_cmp_le_i32_e64 vcc, 58, v33
	v_cndmask_b32_e64 v28, v39, v35, s[6:7]
	v_cmp_le_i32_e64 s[6:7], 57, v33
	v_cndmask_b32_e64 v29, v39, v35, s[8:9]
	v_cndmask_b32_e64 v30, v39, v35, vcc
	s_nop 0
	v_cndmask_b32_e64 v31, v39, v35, s[6:7]
	v_mov_b32_e32 v24, v39
	s_waitcnt lgkmcnt(0)
	v_fma_f32 v204, v3, v15, v9
	v_fma_f32 v212, v2, v14, v8
	v_fma_f32 v205, v3, v10, v9
	v_fma_f32 v213, v2, v11, v8
	v_fma_f32 v206, v3, v188, v9
	v_fma_f32 v214, v2, v189, v8
	v_fma_f32 v207, v3, v190, v9
	v_fma_f32 v215, v2, v191, v8
	v_fma_f32 v208, v3, v192, v9
	v_fma_f32 v216, v2, v193, v8
	v_fma_f32 v209, v3, v194, v9
	v_fma_f32 v217, v2, v195, v8
	v_fma_f32 v210, v3, v196, v9
	v_fma_f32 v218, v2, v197, v8
	v_fma_f32 v211, v3, v198, v9
	v_fma_f32 v219, v2, v199, v8
	v_fma_f32 v204, v5, v10, v204
	v_fma_f32 v212, v4, v11, v212
	v_fma_f32 v205, v5, v188, v205
	v_fma_f32 v213, v4, v189, v213
	v_fma_f32 v206, v5, v190, v206
	v_fma_f32 v214, v4, v191, v214
	v_fma_f32 v207, v5, v192, v207
	v_fma_f32 v215, v4, v193, v215
	v_fma_f32 v208, v5, v194, v208
	v_fma_f32 v216, v4, v195, v216
	v_fma_f32 v209, v5, v196, v209
	v_fma_f32 v217, v4, v197, v217
	v_fma_f32 v210, v5, v198, v210
	v_fma_f32 v218, v4, v199, v218
	v_fma_f32 v211, v5, v200, v211
	v_fma_f32 v219, v4, v201, v219
	v_fma_f32 v204, v7, v188, v204
	v_fma_f32 v212, v6, v189, v212
	v_fma_f32 v205, v7, v190, v205
	v_fma_f32 v213, v6, v191, v213
	v_fma_f32 v206, v7, v192, v206
	v_fma_f32 v214, v6, v193, v214
	v_fma_f32 v207, v7, v194, v207
	v_fma_f32 v215, v6, v195, v215
	v_fma_f32 v208, v7, v196, v208
	v_fma_f32 v216, v6, v197, v216
	v_fma_f32 v209, v7, v198, v209
	v_fma_f32 v217, v6, v199, v217
	v_fma_f32 v210, v7, v200, v210
	v_fma_f32 v218, v6, v201, v218
	v_fma_f32 v211, v7, v202, v211
	v_fma_f32 v219, v6, v203, v219
	v_mul_f32_e32 v220, 0xbfb8aa3b, v204
	v_mul_f32_e32 v221, 0xbfb8aa3b, v205
	v_mul_f32_e32 v222, 0xbfb8aa3b, v206
	v_mul_f32_e32 v223, 0xbfb8aa3b, v207
	v_mul_f32_e32 v224, 0xbfb8aa3b, v208
	v_mul_f32_e32 v225, 0xbfb8aa3b, v209
	v_mul_f32_e32 v226, 0xbfb8aa3b, v210
	v_mul_f32_e32 v227, 0xbfb8aa3b, v211
	v_exp_f32_e32 v220, v220
	v_exp_f32_e32 v221, v221
	v_exp_f32_e32 v222, v222
	v_exp_f32_e32 v223, v223
	v_exp_f32_e32 v224, v224
	v_exp_f32_e32 v225, v225
	v_exp_f32_e32 v226, v226
	v_exp_f32_e32 v227, v227
	v_add_f32_e32 v220, 1.0, v220
	v_add_f32_e32 v221, 1.0, v221
	v_add_f32_e32 v222, 1.0, v222
	v_add_f32_e32 v223, 1.0, v223
	v_add_f32_e32 v224, 1.0, v224
	v_add_f32_e32 v225, 1.0, v225
	v_add_f32_e32 v226, 1.0, v226
	v_add_f32_e32 v227, 1.0, v227
	v_rcp_f32_e32 v220, v220
	v_rcp_f32_e32 v221, v221
	v_rcp_f32_e32 v222, v222
	v_rcp_f32_e32 v223, v223
	v_rcp_f32_e32 v224, v224
	v_rcp_f32_e32 v225, v225
	v_rcp_f32_e32 v226, v226
	v_rcp_f32_e32 v227, v227
	v_mov_b32_e32 v15, v200
	v_mov_b32_e32 v10, v202
	v_mov_b32_e32 v14, v201
	v_mov_b32_e32 v11, v203
	v_mul_f32_e32 v204, v204, v220
	v_mul_f32_e32 v205, v205, v221
	v_mul_f32_e32 v206, v206, v222
	v_mul_f32_e32 v207, v207, v223
	v_mul_f32_e32 v208, v208, v224
	v_mul_f32_e32 v209, v209, v225
	v_mul_f32_e32 v210, v210, v226
	v_mul_f32_e32 v211, v211, v227
	v_mul_f32_e32 v212, v212, v204
	v_mul_f32_e32 v213, v213, v205
	v_mul_f32_e32 v214, v214, v206
	v_mul_f32_e32 v215, v215, v207
	v_mul_f32_e32 v216, v216, v208
	v_mul_f32_e32 v217, v217, v209
	v_mul_f32_e32 v218, v218, v210
	v_mul_f32_e32 v219, v219, v211
	v_cvt_pk_bf16_f32 v212, v212, v213
	v_cvt_pk_bf16_f32 v214, v214, v215
	v_cvt_pk_bf16_f32 v216, v216, v217
	v_cvt_pk_bf16_f32 v218, v218, v219
	v_cmp_gt_i32_e32 vcc, 8, v34
	s_cmp_lg_u64 vcc, 0
	s_cbranch_scc1 .Lcv12_slow0
	global_store_short v24, v212, s[42:43]
	global_store_short_d16_hi v25, v212, s[42:43] offset:128
	global_store_short v26, v214, s[42:43] offset:256
	global_store_short_d16_hi v27, v214, s[42:43] offset:384
	global_store_short v28, v216, s[42:43] offset:512
	global_store_short_d16_hi v29, v216, s[42:43] offset:640
	global_store_short v30, v218, s[42:43] offset:768
	global_store_short_d16_hi v31, v218, s[42:43] offset:896
	s_branch .Lcv12_next0

.Lcv12_next3:
	s_branch .LBB0_2363
.LBB0_2404:
	s_load_dwordx2 s[26:27], s[0:1], 0xf8
